# plus: input-projection GEMM epilogue batches its rstd loads; S5 prompt prefix loads warmed ahead of their serial loop
# baseline (speedup 1.0000x reference)
; DEVINL void s5_passC_prompt(const Params& p, char* smem, int item) {
;     ...
;   const float4 pw = ((const float4*)(p.ws + OFF_APW))[g * 64 + lane];
;   const float2* hend = (const float2*)(p.ws + OFF_HEND);
;   for (int s2 = 0; s2 < s; ++s2) {
;     float pr = (s2 == 0) ? pw.z : pw.x, pi = (s2 == 0) ? pw.w : pw.y;
;     float2 he = hend[((size_t)bg * 7 + s2) * 64 + lane];
;     float nr = pr * hr - pi * hi + he.x, ni = pr * hi + pi * hr + he.y;
;     hr = nr; hi = ni;
;   }
.LBB0_493:
	v_mov_b32_e32 v3, v0
	s_waitcnt lgkmcnt(0)
	s_barrier
	v_ashrrev_i32_e32 v58, 6, v79
	v_and_b32_e32 v80, 63, v3
	v_mov_b32_e32 v3, v0
	v_and_b32_e32 v63, 7, v79
	v_ashrrev_i32_e32 v68, 6, v3
	v_lshrrev_b32_e32 v3, 1, v79
	v_and_b32_e32 v10, 28, v3
	v_add_u32_e32 v4, v68, v10
	v_lshlrev_b32_e32 v11, 5, v58
	v_mov_b32_e32 v3, v2
	v_add_u32_e32 v62, v4, v11
	v_cmp_eq_u32_e64 s[34:35], 0, v63
	v_cmp_ne_u32_e32 vcc, 0, v63
	v_lshlrev_b32_e32 v5, 6, v4
	v_mov_b64_e32 v[66:67], v[2:3]
	s_and_saveexec_b64 s[36:37], vcc
	s_cbranch_execz .LBB0_499
	v_or_b32_e32 v6, v5, v80
	v_readlane_b32 s0, v194, 51
	v_ashrrev_i32_e32 v7, 31, v6
	v_readlane_b32 s1, v194, 52
	v_lshlrev_b32_e32 v12, 3, v80
	v_mov_b32_e32 v13, v2
	v_lshl_add_u64 v[6:7], v[6:7], 4, s[0:1]
	v_readlane_b32 s0, v194, 53
	v_readlane_b32 s1, v194, 54
	global_load_dwordx2 v[8:9], v[6:7], off offset:8
	v_cmp_ne_u32_e32 vcc, 1, v63
	v_lshl_add_u64 v[12:13], s[0:1], 0, v[12:13]
	s_movk_i32 s0, 0xe00
	v_mad_i64_i32 v[12:13], s[0:1], v62, s0, v[12:13]
	global_load_dwordx2 v[204:205], v[12:13], off offset:512
	global_load_dwordx2 v[206:207], v[12:13], off offset:1024
	global_load_dwordx2 v[208:209], v[12:13], off offset:1536
	global_load_dwordx2 v[210:211], v[12:13], off offset:2048
	global_load_dwordx2 v[212:213], v[12:13], off offset:2560
	global_load_dwordx2 v[214:215], v[12:13], off offset:3072
	global_load_dwordx2 v[12:13], v[12:13], off
	s_waitcnt vmcnt(1)
	v_mul_f32_e32 v3, 0, v8
	v_mul_f32_e32 v15, 0, v9
	v_sub_f32_e32 v14, v3, v15
	v_fmac_f32_e32 v15, 0, v8
	s_waitcnt vmcnt(0)
	v_pk_add_f32 v[66:67], v[12:13], v[14:15]
	s_and_saveexec_b64 s[38:39], vcc
	s_cbranch_execz .LBB0_498
	global_load_dwordx2 v[6:7], v[6:7], off
	v_add3_u32 v10, v68, v11, v10
	s_movk_i32 s0, 0xe00
	v_mad_i64_i32 v[10:11], s[0:1], v10, s0, 0
	v_readlane_b32 s0, v192, 27
	v_and_b32_e32 v3, 7, v75
	v_lshl_or_b32 v10, v80, 3, v10
	v_readlane_b32 s1, v192, 28
	v_add_u32_e32 v3, -1, v3
	v_mov_b32_e32 v12, v67
	v_lshl_add_u64 v[10:11], s[0:1], 0, v[10:11]
	s_mov_b64 s[0:1], 0
	s_waitcnt vmcnt(0)
	v_pk_mov_b32 v[8:9], v[6:7], v[6:7] op_sel:[1,0]

; DEVINL f32x4 mfma16(bf16x8 a, bf16x8 b, f32x4 c) { return __builtin_amdgcn_mfma_f32_16x16x32_bf16(a, b, c, 0, 0, 0); }
; DEVINL int ridx(int r) { return ((r >> 4) << 5) | (r & 15); }
; DEVINL void gemm_loop(f32x4 (&acc)[4][4], const u16* __restrict__ A, int lda, const u16* __restrict__ Bt, int ldb,
;                       int m0, int n0, int k0, int nk, char* smem) {
;     ...
;     for (int ks = 0; ks < 2; ++ks)
; #pragma unroll
;       for (int f = 0; f < 4; ++f) {
;         int ra = wr * 64 + f * 16 + fr, rb = wc * 64 + f * 16 + fr;
;         int ch = ks * 4 + fq;
;         af[ks][f] = *(const bf16x8*)(cur + ra * 128 + ((ch ^ ((ra >> 1) & 7)) << 4));
;         bfr[ks][f] = *(const bf16x8*)(cur + 16384 + rb * 128 + ((ch ^ ((rb >> 1) & 7)) << 4));
;       }
;     __builtin_amdgcn_sched_barrier(0);
; #pragma unroll
;     for (int ks = 0; ks < 2; ++ks)
; #pragma unroll
;       for (int mf = 0; mf < 4; ++mf)
; #pragma unroll
;         for (int nf = 0; nf < 4; ++nf) acc[mf][nf] = mfma16(af[ks][mf], bfr[ks][nf], acc[mf][nf]);
; DEVINL void p1_tile(const Params& p, char* smem, int mt, int nt) {
;     ...
; #pragma unroll
;   for (int mf = 0; mf < 4; ++mf) {
;     const int rb = m0 + wr * 64 + mf * 16 + (lane >> 4) * 4;
;     float rs[4];
; #pragma unroll
;     for (int j = 0; j < 4; ++j) rs[j] = rstd0[ridx(rb) + j];
.Lkp_b1075_last:
	v_mfma_f32_16x16x32_bf16 v[64:67], v[156:159], v[164:167], v[64:67]
	v_mfma_f32_16x16x32_bf16 v[60:63], v[156:159], v[168:171], v[60:63]
	v_mfma_f32_16x16x32_bf16 v[52:55], v[156:159], v[180:183], v[52:55]
	v_mfma_f32_16x16x32_bf16 v[48:51], v[156:159], v[184:187], v[48:51]
	v_mfma_f32_16x16x32_bf16 v[44:47], v[160:163], v[164:167], v[44:47]
	v_mfma_f32_16x16x32_bf16 v[40:43], v[160:163], v[168:171], v[40:43]
	v_mfma_f32_16x16x32_bf16 v[36:39], v[160:163], v[180:183], v[36:39]
	v_mfma_f32_16x16x32_bf16 v[32:35], v[160:163], v[184:187], v[32:35]
	v_mfma_f32_16x16x32_bf16 v[28:31], v[172:175], v[164:167], v[28:31]
	v_mfma_f32_16x16x32_bf16 v[24:27], v[172:175], v[168:171], v[24:27]
	v_mfma_f32_16x16x32_bf16 v[20:23], v[172:175], v[180:183], v[20:23]
	v_mfma_f32_16x16x32_bf16 v[16:19], v[172:175], v[184:187], v[16:19]
	v_mfma_f32_16x16x32_bf16 v[12:15], v[176:179], v[164:167], v[12:15]
	v_mfma_f32_16x16x32_bf16 v[8:11], v[176:179], v[168:171], v[8:11]
	v_mfma_f32_16x16x32_bf16 v[4:7], v[176:179], v[180:183], v[4:7]
	v_mfma_f32_16x16x32_bf16 v[56:59], v[176:179], v[184:187], v[56:59]
	s_mov_b32 s1, 0x8000
	v_add_u32_e32 v68, s1, v91
	v_add_u32_e32 v87, v68, v88
	s_waitcnt vmcnt(0)
	s_barrier
	v_add_u32_e32 v91, v68, v89
	ds_read_b128 v[68:71], v87
	ds_read_b128 v[72:75], v87 offset:2048
	ds_read_b128 v[76:79], v91 offset:16384
	ds_read_b128 v[80:83], v91 offset:18432
	ds_read_b128 v[106:109], v87 offset:4096
	ds_read_b128 v[110:113], v87 offset:6144
	ds_read_b128 v[132:135], v91 offset:20480
	ds_read_b128 v[136:139], v91 offset:22528
	v_add_u32_e32 v87, s1, v90
	v_add_u32_e32 v102, v87, v88
	v_add_u32_e32 v87, v87, v89
	ds_read_b128 v[88:91], v102
	ds_read_b128 v[140:143], v102 offset:2048
	ds_read_b128 v[144:147], v87 offset:16384
	ds_read_b128 v[148:151], v87 offset:18432
	ds_read_b128 v[152:155], v102 offset:4096
	ds_read_b128 v[156:159], v102 offset:6144
	ds_read_b128 v[160:163], v87 offset:20480
	ds_read_b128 v[164:167], v87 offset:22528
	s_waitcnt lgkmcnt(13)
	v_mfma_f32_16x16x32_bf16 v[64:67], v[68:71], v[76:79], v[64:67]
	v_readlane_b32 s0, v194, 59
	v_readlane_b32 s1, v194, 60
	v_cmp_lt_i32_e64 s[46:47], 3, v84
	s_waitcnt lgkmcnt(12)
	v_mfma_f32_16x16x32_bf16 v[60:63], v[68:71], v[80:83], v[60:63]
	v_cmp_lt_u32_e64 s[44:45], 7, v84
	v_cmp_lt_u32_e64 s[42:43], 11, v84
	v_cmp_lt_u32_e64 s[40:41], 15, v84
	s_waitcnt lgkmcnt(9)
	v_mfma_f32_16x16x32_bf16 v[52:55], v[68:71], v[132:135], v[52:55]
	v_cmp_lt_i32_e64 s[36:37], 1, v84
	s_waitcnt lgkmcnt(8)
	v_mfma_f32_16x16x32_bf16 v[48:51], v[68:71], v[136:139], v[48:51]
	v_mov_b32_e32 v69, v0
	v_mov_b32_e32 v68, v0
	v_mfma_f32_16x16x32_bf16 v[44:47], v[72:75], v[76:79], v[44:47]
	v_and_b32_e32 v70, 15, v69
	v_mfma_f32_16x16x32_bf16 v[40:43], v[72:75], v[80:83], v[40:43]
	v_mfma_f32_16x16x32_bf16 v[36:39], v[72:75], v[132:135], v[36:39]
	v_mfma_f32_16x16x32_bf16 v[20:23], v[106:109], v[132:135], v[20:23]
	v_mfma_f32_16x16x32_bf16 v[4:7], v[110:113], v[132:135], v[4:7]
	s_waitcnt lgkmcnt(5)
	v_mfma_f32_16x16x32_bf16 v[132:135], v[88:91], v[144:147], v[64:67]
	s_waitcnt lgkmcnt(4)
	v_mfma_f32_16x16x32_bf16 v[64:67], v[88:91], v[148:151], v[60:63]
	s_waitcnt lgkmcnt(1)
	v_mfma_f32_16x16x32_bf16 v[60:63], v[88:91], v[160:163], v[52:55]
	s_waitcnt lgkmcnt(0)
	v_mfma_f32_16x16x32_bf16 v[52:55], v[88:91], v[164:167], v[48:51]
	s_nop 2
	v_ashrrev_i32_e32 v48, 1, v68
	v_mfma_f32_16x16x32_bf16 v[28:31], v[106:109], v[76:79], v[28:31]
	v_and_b32_e32 v68, 64, v68
	v_or3_b32 v68, v70, v68, v85
	v_mfma_f32_16x16x32_bf16 v[24:27], v[106:109], v[80:83], v[24:27]
	v_mfma_f32_16x16x32_bf16 v[16:19], v[106:109], v[136:139], v[16:19]
	v_mfma_f32_16x16x32_bf16 v[12:15], v[110:113], v[76:79], v[12:15]
	v_mfma_f32_16x16x32_bf16 v[8:11], v[110:113], v[80:83], v[8:11]
	v_mfma_f32_16x16x32_bf16 v[108:111], v[110:113], v[136:139], v[56:59]
	s_nop 2
	v_and_b32_e32 v56, 0xffffffc0, v48
	v_mfma_f32_16x16x32_bf16 v[48:51], v[140:143], v[144:147], v[44:47]
	v_add_u32_e32 v102, v56, v86
	s_nop 1
	v_lshrrev_b32_e32 v44, 2, v69
	v_and_b32_e32 v91, 12, v44
	v_mfma_f32_16x16x32_bf16 v[44:47], v[140:143], v[148:151], v[40:43]
	v_and_b32_e32 v69, 1, v69
	v_lshlrev_b32_e32 v105, 1, v69
	v_cmp_eq_u32_e64 s[38:39], 0, v69
	v_lshl_or_b32 v40, v102, 1, v91
	v_ashrrev_i32_e32 v41, 31, v40
	v_lshl_add_u64 v[56:57], v[40:41], 2, s[0:1]
	global_load_dwordx4 v[204:207], v[56:57], off offset:128
	global_load_dwordx4 v[208:211], v[56:57], off offset:256
	global_load_dwordx4 v[212:215], v[56:57], off offset:384
	global_load_dwordx4 v[56:59], v[56:57], off
	v_mfma_f32_16x16x32_bf16 v[32:35], v[72:75], v[136:139], v[32:35]
	v_or_b32_e32 v72, v102, v91
	v_or_b32_e32 v76, v72, v105
	v_ashrrev_i32_e32 v77, 31, v76
	v_mfma_f32_16x16x32_bf16 v[40:43], v[140:143], v[160:163], v[36:39]
	v_lshlrev_b64 v[70:71], 10, v[76:77]
	v_or_b32_e32 v76, 1, v76
	v_ashrrev_i32_e32 v77, 31, v76
	v_mfma_f32_16x16x32_bf16 v[36:39], v[140:143], v[164:167], v[32:35]
	v_lshlrev_b64 v[82:83], 10, v[76:77]
	v_lshl_add_u64 v[74:75], s[96:97], 0, v[70:71]
	v_lshl_add_u64 v[76:77], s[96:97], 0, v[82:83]
	v_mfma_f32_16x16x32_bf16 v[32:35], v[152:155], v[144:147], v[28:31]
	v_lshl_add_u64 v[78:79], s[92:93], 0, v[70:71]
	v_lshl_add_u64 v[80:81], s[92:93], 0, v[82:83]
	v_ashrrev_i32_e32 v73, 31, v72
	v_mfma_f32_16x16x32_bf16 v[28:31], v[152:155], v[148:151], v[24:27]
	s_waitcnt vmcnt(0)
	v_mul_f32_e32 v106, v132, v56
	v_mfma_f32_16x16x32_bf16 v[24:27], v[152:155], v[160:163], v[20:23]
	v_mul_f32_e32 v90, v133, v57
	v_mul_f32_e32 v89, v134, v58
	v_mul_f32_e32 v88, v135, v59
	v_mfma_f32_16x16x32_bf16 v[20:23], v[152:155], v[164:167], v[16:19]
	v_mfma_f32_16x16x32_bf16 v[16:19], v[156:159], v[144:147], v[12:15]
	v_mfma_f32_16x16x32_bf16 v[12:15], v[156:159], v[148:151], v[8:11]
	v_mfma_f32_16x16x32_bf16 v[8:11], v[156:159], v[160:163], v[4:7]
	v_mfma_f32_16x16x32_bf16 v[4:7], v[156:159], v[164:167], v[108:111]
	s_and_saveexec_b64 s[0:1], s[46:47]
	s_xor_b64 s[66:67], exec, s[0:1]
	s_cbranch_execz .LBB0_1092
; DEVINL void p1_tile(const Params& p, char* smem, int mt, int nt) {
;     ...
;       if (nt < 4) {
;         store_pairs(qk, 512, rb, col, v[0], v[1], v[2], v[3]);
;         if (nt >= 2) *(uint2*)(kT + (size_t)(col - 256) * LDT + rb) = make_uint2(pack2(v[0], v[1]), pack2(v[2], v[3]));
;       } else if (nt < 8) {
;         *(uint2*)(vT + (size_t)(col - 512) * LDT + rb) = make_uint2(pack2(v[0], v[1]), pack2(v[2], v[3]));
;       } else if (nt < 12) {
;         store_pairs(gb, 512, rb, col - 1024, v[0], v[1], v[2], v[3]);
;       } else if (nt < 16) {
;         store_pairs(ub, 512, rb, col - 1536, v[0], v[1], v[2], v[3]);
;       } else if (col < 2064) {
; #pragma unroll
;         for (int j = 0; j < 4; ++j) gk[(size_t)(rb + j) * 16 + (col - 2048)] = v[j];
;       }
	s_and_saveexec_b64 s[0:1], s[44:45]
	s_xor_b64 s[90:91], exec, s[0:1]
	s_cbranch_execz .LBB0_1089
	s_and_saveexec_b64 s[0:1], s[42:43]
	s_xor_b64 s[86:87], exec, s[0:1]
	s_cbranch_execz .LBB0_1086
	s_and_saveexec_b64 s[0:1], s[40:41]
	s_xor_b64 s[88:89], exec, s[0:1]
	s_cbranch_execz .LBB0_1083
	s_movk_i32 s0, 0x810
	v_cmp_gt_i32_e32 vcc, s0, v68
	s_and_saveexec_b64 s[0:1], vcc
	s_cbranch_execz .LBB0_1082
	v_mov_b32_e32 v69, v2
	v_lshl_add_u64 v[84:85], v[68:69], 2, s[50:51]
	v_lshlrev_b64 v[86:87], 6, v[72:73]
	v_lshl_add_u64 v[86:87], v[84:85], 0, v[86:87]
	v_add_co_u32_e32 v86, vcc, 0x1921000, v86
	s_nop 1
	v_addc_co_u32_e32 v87, vcc, 0, v87, vcc
	global_store_dword v[86:87], v106, off offset:2560
	v_or_b32_e32 v86, 1, v72
	v_ashrrev_i32_e32 v87, 31, v86
	v_lshlrev_b64 v[86:87], 6, v[86:87]
	v_lshl_add_u64 v[86:87], v[84:85], 0, v[86:87]
	v_add_co_u32_e32 v86, vcc, 0x1921000, v86
	s_nop 1
	v_addc_co_u32_e32 v87, vcc, 0, v87, vcc
	global_store_dword v[86:87], v90, off offset:2560
	v_or_b32_e32 v86, 2, v72
	v_ashrrev_i32_e32 v87, 31, v86
	v_lshlrev_b64 v[86:87], 6, v[86:87]
	v_lshl_add_u64 v[86:87], v[84:85], 0, v[86:87]
	v_add_co_u32_e32 v86, vcc, 0x1921000, v86
	s_nop 1
	v_addc_co_u32_e32 v87, vcc, 0, v87, vcc
	global_store_dword v[86:87], v89, off offset:2560
	v_or_b32_e32 v86, 3, v72
	v_ashrrev_i32_e32 v87, 31, v86
	v_lshlrev_b64 v[86:87], 6, v[86:87]
	v_lshl_add_u64 v[84:85], v[84:85], 0, v[86:87]
	v_add_co_u32_e32 v84, vcc, 0x1921000, v84
	s_nop 1
	v_addc_co_u32_e32 v85, vcc, 0, v85, vcc
	global_store_dword v[84:85], v88, off offset:2560

; DEVINL int ridx(int r) { return ((r >> 4) << 5) | (r & 15); }
; DEVINL void p1_tile(const Params& p, char* smem, int mt, int nt) {
;     ...
;     const int rb = m0 + wr * 64 + mf * 16 + (lane >> 4) * 4;
;     float rs[4];
; #pragma unroll
;     for (int j = 0; j < 4; ++j) rs[j] = rstd0[ridx(rb) + j];
; #pragma unroll
;     for (int nf = 0; nf < 4; ++nf) {
;       const int col = n0 + wc * 64 + nf * 16 + (lane & 15);
;       float v[4];
; #pragma unroll
;       for (int j = 0; j < 4; ++j) v[j] = acc[mf][nf][j] * rs[j];
;       if (nt < 4) {
;         store_pairs(qk, 512, rb, col, v[0], v[1], v[2], v[3]);
;         if (nt >= 2) *(uint2*)(kT + (size_t)(col - 256) * LDT + rb) = make_uint2(pack2(v[0], v[1]), pack2(v[2], v[3]));
;       } else if (nt < 8) {
;         *(uint2*)(vT + (size_t)(col - 512) * LDT + rb) = make_uint2(pack2(v[0], v[1]), pack2(v[2], v[3]));
;       } else if (nt < 12) {
;         store_pairs(gb, 512, rb, col - 1024, v[0], v[1], v[2], v[3]);
;       } else if (nt < 16) {
;         store_pairs(ub, 512, rb, col - 1536, v[0], v[1], v[2], v[3]);
;       } else if (col < 2064) {
; #pragma unroll
;         for (int j = 0; j < 4; ++j) gk[(size_t)(rb + j) * 16 + (col - 2048)] = v[j];
;       }
.LBB0_1156:
	s_or_b64 exec, exec, s[0:1]
	v_or_b32_e32 v57, 16, v102
	v_lshl_or_b32 v52, v57, 1, v91
	v_readlane_b32 s0, v194, 59
	v_ashrrev_i32_e32 v53, 31, v52
	v_readlane_b32 s1, v194, 60
	v_or_b32_e32 v58, v57, v91
	v_or_b32_e32 v62, v58, v105
	v_lshl_add_u64 v[52:53], v[52:53], 2, s[0:1]
	v_mov_b32_e32 v52, v204
	v_mov_b32_e32 v53, v205
	v_mov_b32_e32 v54, v206
	v_mov_b32_e32 v55, v207
	v_or_b32_e32 v66, 1, v62
	v_ashrrev_i32_e32 v63, 31, v62
	v_ashrrev_i32_e32 v67, 31, v66
	v_lshlrev_b64 v[76:77], 10, v[62:63]
	v_lshlrev_b64 v[78:79], 10, v[66:67]
	v_ashrrev_i32_e32 v59, 31, v58
	v_lshl_add_u64 v[62:63], s[96:97], 0, v[76:77]
	v_lshl_add_u64 v[72:73], s[92:93], 0, v[76:77]
	v_lshl_add_u64 v[66:67], s[96:97], 0, v[78:79]
	v_lshl_add_u64 v[74:75], s[92:93], 0, v[78:79]
	v_mul_f32_e32 v80, v48, v52
	v_mul_f32_e32 v65, v49, v53
	v_mul_f32_e32 v61, v50, v54
	v_mul_f32_e32 v57, v51, v55
	s_and_saveexec_b64 s[0:1], s[46:47]
	s_xor_b64 s[66:67], exec, s[0:1]
	s_cbranch_execz .LBB0_1172
	s_and_saveexec_b64 s[0:1], s[44:45]
	s_xor_b64 s[90:91], exec, s[0:1]
	s_cbranch_execz .LBB0_1169
	s_and_saveexec_b64 s[0:1], s[42:43]
	s_xor_b64 s[86:87], exec, s[0:1]
	s_cbranch_execz .LBB0_1166
	s_and_saveexec_b64 s[0:1], s[40:41]
	s_xor_b64 s[88:89], exec, s[0:1]
	s_cbranch_execz .LBB0_1163
	s_movk_i32 s0, 0x810
	v_cmp_gt_i32_e32 vcc, s0, v68
	s_and_saveexec_b64 s[0:1], vcc
	s_cbranch_execz .LBB0_1162
	v_mov_b32_e32 v69, v2
	v_lshl_add_u64 v[48:49], v[68:69], 2, s[50:51]
	v_lshlrev_b64 v[50:51], 6, v[58:59]
	v_lshl_add_u64 v[50:51], v[48:49], 0, v[50:51]
	v_add_co_u32_e32 v50, vcc, 0x1921000, v50
	s_nop 1
	v_addc_co_u32_e32 v51, vcc, 0, v51, vcc
	global_store_dword v[50:51], v80, off offset:2560
	v_or_b32_e32 v50, 1, v58
	v_ashrrev_i32_e32 v51, 31, v50
	v_lshlrev_b64 v[50:51], 6, v[50:51]
	v_lshl_add_u64 v[50:51], v[48:49], 0, v[50:51]
	v_add_co_u32_e32 v50, vcc, 0x1921000, v50
	s_nop 1
	v_addc_co_u32_e32 v51, vcc, 0, v51, vcc
	global_store_dword v[50:51], v65, off offset:2560
	v_or_b32_e32 v50, 2, v58
	v_ashrrev_i32_e32 v51, 31, v50
	v_lshlrev_b64 v[50:51], 6, v[50:51]
	v_lshl_add_u64 v[50:51], v[48:49], 0, v[50:51]
	v_add_co_u32_e32 v50, vcc, 0x1921000, v50
	s_nop 1
	v_addc_co_u32_e32 v51, vcc, 0, v51, vcc
	global_store_dword v[50:51], v61, off offset:2560
	v_or_b32_e32 v50, 3, v58
	v_ashrrev_i32_e32 v51, 31, v50
	v_lshlrev_b64 v[50:51], 6, v[50:51]
	v_lshl_add_u64 v[48:49], v[48:49], 0, v[50:51]
	v_add_co_u32_e32 v48, vcc, 0x1921000, v48
	s_nop 1
	v_addc_co_u32_e32 v49, vcc, 0, v49, vcc
	global_store_dword v[48:49], v57, off offset:2560

; DEVINL int ridx(int r) { return ((r >> 4) << 5) | (r & 15); }
; DEVINL void p1_tile(const Params& p, char* smem, int mt, int nt) {
;     ...
;     const int rb = m0 + wr * 64 + mf * 16 + (lane >> 4) * 4;
;     float rs[4];
; #pragma unroll
;     for (int j = 0; j < 4; ++j) rs[j] = rstd0[ridx(rb) + j];
; #pragma unroll
;     for (int nf = 0; nf < 4; ++nf) {
;       const int col = n0 + wc * 64 + nf * 16 + (lane & 15);
;       float v[4];
; #pragma unroll
;       for (int j = 0; j < 4; ++j) v[j] = acc[mf][nf][j] * rs[j];
;       if (nt < 4) {
;         store_pairs(qk, 512, rb, col, v[0], v[1], v[2], v[3]);
;         if (nt >= 2) *(uint2*)(kT + (size_t)(col - 256) * LDT + rb) = make_uint2(pack2(v[0], v[1]), pack2(v[2], v[3]));
;       } else if (nt < 8) {
;         *(uint2*)(vT + (size_t)(col - 512) * LDT + rb) = make_uint2(pack2(v[0], v[1]), pack2(v[2], v[3]));
;       } else if (nt < 12) {
;         store_pairs(gb, 512, rb, col - 1024, v[0], v[1], v[2], v[3]);
;       } else if (nt < 16) {
;         store_pairs(ub, 512, rb, col - 1536, v[0], v[1], v[2], v[3]);
;       } else if (col < 2064) {
; #pragma unroll
;         for (int j = 0; j < 4; ++j) gk[(size_t)(rb + j) * 16 + (col - 2048)] = v[j];
;       }
.LBB0_1236:
	s_or_b64 exec, exec, s[0:1]
	v_or_b32_e32 v40, 32, v102
	v_lshl_or_b32 v36, v40, 1, v91
	v_readlane_b32 s0, v194, 59
	v_ashrrev_i32_e32 v37, 31, v36
	v_readlane_b32 s1, v194, 60
	v_or_b32_e32 v40, v40, v91
	v_or_b32_e32 v42, v40, v105
	v_lshl_add_u64 v[36:37], v[36:37], 2, s[0:1]
	v_mov_b32_e32 v36, v208
	v_mov_b32_e32 v37, v209
	v_mov_b32_e32 v38, v210
	v_mov_b32_e32 v39, v211
	v_or_b32_e32 v44, 1, v42
	v_ashrrev_i32_e32 v43, 31, v42
	v_ashrrev_i32_e32 v45, 31, v44
	v_lshlrev_b64 v[50:51], 10, v[42:43]
	v_lshlrev_b64 v[52:53], 10, v[44:45]
	v_ashrrev_i32_e32 v41, 31, v40
	v_lshl_add_u64 v[42:43], s[96:97], 0, v[50:51]
	v_lshl_add_u64 v[46:47], s[92:93], 0, v[50:51]
	v_lshl_add_u64 v[44:45], s[96:97], 0, v[52:53]
	v_lshl_add_u64 v[48:49], s[92:93], 0, v[52:53]
	v_mul_f32_e32 v58, v32, v36
	v_mul_f32_e32 v57, v33, v37
	v_mul_f32_e32 v55, v34, v38
	v_mul_f32_e32 v54, v35, v39
	s_and_saveexec_b64 s[0:1], s[46:47]
	s_xor_b64 s[66:67], exec, s[0:1]
	s_cbranch_execz .LBB0_1252
	s_and_saveexec_b64 s[0:1], s[44:45]
	s_xor_b64 s[90:91], exec, s[0:1]
	s_cbranch_execz .LBB0_1249
	s_and_saveexec_b64 s[0:1], s[42:43]
	s_xor_b64 s[86:87], exec, s[0:1]
	s_cbranch_execz .LBB0_1246
	s_and_saveexec_b64 s[0:1], s[40:41]
	s_xor_b64 s[88:89], exec, s[0:1]
	s_cbranch_execz .LBB0_1243
	s_movk_i32 s0, 0x810
	v_cmp_gt_i32_e32 vcc, s0, v68
	s_and_saveexec_b64 s[0:1], vcc
	s_cbranch_execz .LBB0_1242
	v_mov_b32_e32 v69, v2
	v_lshl_add_u64 v[32:33], v[68:69], 2, s[50:51]
	v_lshlrev_b64 v[34:35], 6, v[40:41]
	v_lshl_add_u64 v[34:35], v[32:33], 0, v[34:35]
	v_add_co_u32_e32 v34, vcc, 0x1921000, v34
	s_nop 1
	v_addc_co_u32_e32 v35, vcc, 0, v35, vcc
	global_store_dword v[34:35], v58, off offset:2560
	v_or_b32_e32 v34, 1, v40
	v_ashrrev_i32_e32 v35, 31, v34
	v_lshlrev_b64 v[34:35], 6, v[34:35]
	v_lshl_add_u64 v[34:35], v[32:33], 0, v[34:35]
	v_add_co_u32_e32 v34, vcc, 0x1921000, v34
	s_nop 1
	v_addc_co_u32_e32 v35, vcc, 0, v35, vcc
	global_store_dword v[34:35], v57, off offset:2560
	v_or_b32_e32 v34, 2, v40
	v_ashrrev_i32_e32 v35, 31, v34
	v_lshlrev_b64 v[34:35], 6, v[34:35]
	v_lshl_add_u64 v[34:35], v[32:33], 0, v[34:35]
	v_add_co_u32_e32 v34, vcc, 0x1921000, v34
	s_nop 1
	v_addc_co_u32_e32 v35, vcc, 0, v35, vcc
	global_store_dword v[34:35], v55, off offset:2560
	v_or_b32_e32 v34, 3, v40
	v_ashrrev_i32_e32 v35, 31, v34
	v_lshlrev_b64 v[34:35], 6, v[34:35]
	v_lshl_add_u64 v[32:33], v[32:33], 0, v[34:35]
	v_add_co_u32_e32 v32, vcc, 0x1921000, v32
	s_nop 1
	v_addc_co_u32_e32 v33, vcc, 0, v33, vcc
	global_store_dword v[32:33], v54, off offset:2560

; DEVINL int ridx(int r) { return ((r >> 4) << 5) | (r & 15); }
; DEVINL void p1_tile(const Params& p, char* smem, int mt, int nt) {
;     ...
;     const int rb = m0 + wr * 64 + mf * 16 + (lane >> 4) * 4;
;     float rs[4];
; #pragma unroll
;     for (int j = 0; j < 4; ++j) rs[j] = rstd0[ridx(rb) + j];
; #pragma unroll
;     for (int nf = 0; nf < 4; ++nf) {
;       const int col = n0 + wc * 64 + nf * 16 + (lane & 15);
;       float v[4];
; #pragma unroll
;       for (int j = 0; j < 4; ++j) v[j] = acc[mf][nf][j] * rs[j];
;       if (nt < 4) {
;         store_pairs(qk, 512, rb, col, v[0], v[1], v[2], v[3]);
;         if (nt >= 2) *(uint2*)(kT + (size_t)(col - 256) * LDT + rb) = make_uint2(pack2(v[0], v[1]), pack2(v[2], v[3]));
;       } else if (nt < 8) {
;         *(uint2*)(vT + (size_t)(col - 512) * LDT + rb) = make_uint2(pack2(v[0], v[1]), pack2(v[2], v[3]));
;       } else if (nt < 12) {
;         store_pairs(gb, 512, rb, col - 1024, v[0], v[1], v[2], v[3]);
;       } else if (nt < 16) {
;         store_pairs(ub, 512, rb, col - 1536, v[0], v[1], v[2], v[3]);
;       } else if (col < 2064) {
; #pragma unroll
;         for (int j = 0; j < 4; ++j) gk[(size_t)(rb + j) * 16 + (col - 2048)] = v[j];
;       }
.LBB0_1316:
	s_or_b64 exec, exec, s[0:1]
	v_or_b32_e32 v24, 48, v102
	v_lshl_or_b32 v20, v24, 1, v91
	v_readlane_b32 s0, v194, 59
	v_ashrrev_i32_e32 v21, 31, v20
	v_readlane_b32 s1, v194, 60
	v_or_b32_e32 v24, v24, v91
	v_or_b32_e32 v26, v24, v105
	v_lshl_add_u64 v[20:21], v[20:21], 2, s[0:1]
	v_mov_b32_e32 v20, v212
	v_mov_b32_e32 v21, v213
	v_mov_b32_e32 v22, v214
	v_mov_b32_e32 v23, v215
	v_or_b32_e32 v28, 1, v26
	v_ashrrev_i32_e32 v27, 31, v26
	v_ashrrev_i32_e32 v29, 31, v28
	v_lshlrev_b64 v[34:35], 10, v[26:27]
	v_lshlrev_b64 v[36:37], 10, v[28:29]
	v_ashrrev_i32_e32 v25, 31, v24
	v_lshl_add_u64 v[26:27], s[96:97], 0, v[34:35]
	v_lshl_add_u64 v[30:31], s[92:93], 0, v[34:35]
	v_lshl_add_u64 v[28:29], s[96:97], 0, v[36:37]
	v_lshl_add_u64 v[32:33], s[92:93], 0, v[36:37]
	v_mul_f32_e32 v41, v16, v20
	v_mul_f32_e32 v40, v17, v21
	v_mul_f32_e32 v39, v18, v22
	v_mul_f32_e32 v38, v19, v23
	s_and_saveexec_b64 s[0:1], s[46:47]
	s_xor_b64 s[66:67], exec, s[0:1]
	s_cbranch_execz .LBB0_1332
	s_and_saveexec_b64 s[0:1], s[44:45]
	s_xor_b64 s[90:91], exec, s[0:1]
	s_cbranch_execz .LBB0_1329
	s_and_saveexec_b64 s[0:1], s[42:43]
	s_xor_b64 s[86:87], exec, s[0:1]
	s_cbranch_execz .LBB0_1326
	s_and_saveexec_b64 s[0:1], s[40:41]
	s_xor_b64 s[88:89], exec, s[0:1]
	s_cbranch_execz .LBB0_1323
	s_movk_i32 s0, 0x810
	v_cmp_gt_i32_e32 vcc, s0, v68
	s_and_saveexec_b64 s[0:1], vcc
	s_cbranch_execz .LBB0_1322
	v_mov_b32_e32 v69, v2
	v_lshl_add_u64 v[16:17], v[68:69], 2, s[50:51]
	v_lshlrev_b64 v[18:19], 6, v[24:25]
	v_lshl_add_u64 v[18:19], v[16:17], 0, v[18:19]
	v_add_co_u32_e32 v18, vcc, 0x1921000, v18
	s_nop 1
	v_addc_co_u32_e32 v19, vcc, 0, v19, vcc
	global_store_dword v[18:19], v41, off offset:2560
	v_or_b32_e32 v18, 1, v24
	v_ashrrev_i32_e32 v19, 31, v18
	v_lshlrev_b64 v[18:19], 6, v[18:19]
	v_lshl_add_u64 v[18:19], v[16:17], 0, v[18:19]
	v_add_co_u32_e32 v18, vcc, 0x1921000, v18
	s_nop 1
	v_addc_co_u32_e32 v19, vcc, 0, v19, vcc
	global_store_dword v[18:19], v40, off offset:2560
	v_or_b32_e32 v18, 2, v24
	v_ashrrev_i32_e32 v19, 31, v18
	v_lshlrev_b64 v[18:19], 6, v[18:19]
	v_lshl_add_u64 v[18:19], v[16:17], 0, v[18:19]
	v_add_co_u32_e32 v18, vcc, 0x1921000, v18
	s_nop 1
	v_addc_co_u32_e32 v19, vcc, 0, v19, vcc
	global_store_dword v[18:19], v39, off offset:2560
	v_or_b32_e32 v18, 3, v24
	v_ashrrev_i32_e32 v19, 31, v18
	v_lshlrev_b64 v[18:19], 6, v[18:19]
	v_lshl_add_u64 v[16:17], v[16:17], 0, v[18:19]
	v_add_co_u32_e32 v16, vcc, 0x1921000, v16
	s_nop 1
	v_addc_co_u32_e32 v17, vcc, 0, v17, vcc
	global_store_dword v[16:17], v38, off offset:2560
